# NA bias/mask: 64 exec-masked LDS-read blocks replaced by batched unconditional reads (rp[.][31] = -inf sentinel), on top of phase-split GEMM loops
# speedup vs baseline: 1.0529x; 1.0132x over previous
; __device__ __forceinline__ int otid() { int t = threadIdx.x; asm volatile("" : "+v"(t)); return t; }
; __device__ __forceinline__ void na_item(const Params& p, int item, char* lds) {
;   const int tid = otid(), lane = tid & 63, wave = tid >> 6;
;   const int lr = lane & 15, lq = lane >> 4;
;   const int h = item & 7, r = (item >> 3) & 31, b = item >> 8;
;   const int rs = min(max(r - 4, 0), 24);
;   const int n = wave & 3, half = wave >> 2;
;   const u16* Q = (const u16*)(p.ws + OFF_Q);
;   const u16* K = (const u16*)(p.ws + OFF_K);
;   const u16* VT = (const u16*)(p.ws + OFF_VT);
;   const u16* KC = (const u16*)(p.ws + OFF_KC);
;   const u16* VCT = (const u16*)(p.ws + OFF_VCT);
;   u16* NAO = (u16*)(p.ws + OFF_NA);
;   float* rp = (float*)(lds + 110592);
;   float* comb = (float*)(lds + 111616);
;   float* ml = comb + 4 * 16 * 64;
; #pragma unroll
;   for (int i = 0; i < 8; ++i) {
;     const int ch = tid + i * NTHR; const int key = ch >> 3, c8 = ch & 7;
;     const int tok = b * 2048 + (rs + (key >> 6)) * 64 + (key & 63);
;     const uint4 v = *(const uint4*)(K + (size_t)tok * 512 + h * 64 + c8 * 8);
;     *(uint4*)(lds + key * 144 + c8 * 16) = v;
;   }
; #pragma unroll
;   for (int i = 0; i < 4; ++i) {
;     const int ch = tid + i * NTHR; const int m = ch >> 3, c8 = ch & 7;
;     const uint4 v = *(const uint4*)(KC + (size_t)(b * 256 + m) * 512 + h * 64 + c8 * 8);
;     *(uint4*)(lds + (512 + m) * 144 + c8 * 16) = v;
;   }
;   if (tid < 256) {
;     const int i = tid >> 5, ci = tid & 31; const int ri = rs + i - r + 7;
;     rp[tid] = (ci < 31) ? p.in[19][(h * 15 + ri) * 31 + ci] : 0.f;
;   }
.LBB0_506:
	s_cmpk_gt_i32 s78, 0x3ff
	s_mov_b64 s[6:7], -1
	s_cbranch_scc0 .LBB0_654
	v_mov_b32_e32 v147, v153
	s_bfe_u32 s34, s78, 0x50003
	s_add_i32 s8, s78, 0xfffffc00
	v_sub_u32_e64 v0, s34, 4 clamp
	v_add_u32_e32 v20, 0x800, v147
	s_lshr_b32 s38, s8, 8
	v_min_u32_e32 v8, 24, v0
	v_ashrrev_i32_e32 v21, 9, v20
	s_lshl_b32 s39, s38, 11
	v_add_u32_e32 v21, v21, v8
	v_ashrrev_i32_e32 v66, 3, v20
	v_lshl_add_u32 v21, v21, 6, s39
	v_lshlrev_b32_e32 v0, 4, v147
	v_add_u32_e32 v37, 0x200, v147
	v_add_u32_e32 v44, 0x400, v147
	v_add_u32_e32 v45, 0x600, v147
	v_and_or_b32 v22, v66, 63, v21
	v_add_u32_e32 v21, 0xa00, v147
	v_and_b32_e32 v144, 0x70, v0
	v_ashrrev_i32_e32 v0, 9, v147
	v_ashrrev_i32_e32 v2, 9, v37
	v_ashrrev_i32_e32 v10, 9, v44
	v_ashrrev_i32_e32 v12, 9, v45
	v_ashrrev_i32_e32 v24, 9, v21
	s_and_b32 s40, s78, 7
	v_add_u32_e32 v0, v0, v8
	v_add_u32_e32 v2, v2, v8
	v_add_u32_e32 v10, v10, v8
	v_add_u32_e32 v12, v12, v8
	v_add_u32_e32 v24, v24, v8
	s_lshl_b32 s9, s40, 7
	v_ashrrev_i32_e32 v9, 3, v147
	v_lshl_add_u32 v0, v0, 6, s39
	v_ashrrev_i32_e32 v36, 3, v37
	v_lshl_add_u32 v2, v2, 6, s39
	v_ashrrev_i32_e32 v42, 3, v44
	v_lshl_add_u32 v10, v10, 6, s39
	v_ashrrev_i32_e32 v43, 3, v45
	v_lshl_add_u32 v12, v12, 6, s39
	v_ashrrev_i32_e32 v67, 3, v21
	v_lshl_add_u32 v24, v24, 6, s39
	s_add_u32 s6, s2, s9
	v_and_or_b32 v0, v9, 63, v0
	v_and_or_b32 v2, v36, 63, v2
	v_and_or_b32 v10, v42, 63, v10
	v_and_or_b32 v12, v43, 63, v12
	v_and_or_b32 v24, v67, 63, v24
	s_addc_u32 s7, s33, 0
	v_ashrrev_i32_e32 v1, 31, v0
	v_ashrrev_i32_e32 v3, 31, v2
	v_ashrrev_i32_e32 v11, 31, v10
	v_ashrrev_i32_e32 v13, 31, v12
	v_ashrrev_i32_e32 v23, 31, v22
	v_ashrrev_i32_e32 v25, 31, v24
	v_lshl_add_u64 v[18:19], s[6:7], 0, v[144:145]
	v_lshlrev_b64 v[0:1], 10, v[0:1]
	v_lshlrev_b64 v[2:3], 10, v[2:3]
	v_lshlrev_b64 v[10:11], 10, v[10:11]
	v_lshlrev_b64 v[12:13], 10, v[12:13]
	v_lshlrev_b64 v[22:23], 10, v[22:23]
	v_lshlrev_b64 v[24:25], 10, v[24:25]
	v_lshl_add_u64 v[0:1], v[18:19], 0, v[0:1]
	v_lshl_add_u64 v[4:5], v[18:19], 0, v[2:3]
	v_lshl_add_u64 v[10:11], v[18:19], 0, v[10:11]
	v_lshl_add_u64 v[14:15], v[18:19], 0, v[12:13]
	v_lshl_add_u64 v[22:23], v[18:19], 0, v[22:23]
	v_lshl_add_u64 v[26:27], v[18:19], 0, v[24:25]
	v_add_u32_e32 v28, 0xc00, v147
	global_load_dwordx4 v[0:3], v[0:1], off
	s_nop 0
	global_load_dwordx4 v[4:7], v[4:5], off
	s_nop 0
	global_load_dwordx4 v[10:13], v[10:11], off
	s_nop 0
	global_load_dwordx4 v[14:17], v[14:15], off
	s_nop 0
	global_load_dwordx4 v[22:25], v[22:23], off
	s_nop 0
	global_load_dwordx4 v[30:33], v[26:27], off
	v_ashrrev_i32_e32 v26, 9, v28
	v_add_u32_e32 v29, 0xe00, v147
	v_add_u32_e32 v26, v26, v8
	v_ashrrev_i32_e32 v34, 9, v29
	v_ashrrev_i32_e32 v68, 3, v28
	v_lshl_add_u32 v26, v26, 6, s39
	v_add_u32_e32 v34, v34, v8
	v_and_or_b32 v26, v68, 63, v26
	v_ashrrev_i32_e32 v69, 3, v29
	v_lshl_add_u32 v34, v34, 6, s39
	v_ashrrev_i32_e32 v27, 31, v26
	v_and_or_b32 v34, v69, 63, v34
	v_lshlrev_b64 v[26:27], 10, v[26:27]
	v_ashrrev_i32_e32 v35, 31, v34
	v_lshl_add_u64 v[26:27], v[18:19], 0, v[26:27]
	v_lshlrev_b64 v[34:35], 10, v[34:35]
	s_and_b32 s8, s8, 0x1f00
	v_lshl_add_u64 v[18:19], v[18:19], 0, v[34:35]
	global_load_dwordx4 v[38:41], v[26:27], off
	global_load_dwordx4 v[46:49], v[18:19], off
	s_add_u32 s6, s50, s9
	v_add_u32_e32 v26, s8, v9
	s_addc_u32 s7, s51, 0
	v_ashrrev_i32_e32 v27, 31, v26
	v_add_u32_e32 v34, s8, v36
	v_lshl_add_u64 v[18:19], s[6:7], 0, v[144:145]
	v_lshlrev_b64 v[26:27], 10, v[26:27]
	v_ashrrev_i32_e32 v35, 31, v34
	v_lshl_add_u64 v[26:27], v[18:19], 0, v[26:27]
	v_lshlrev_b64 v[34:35], 10, v[34:35]
	v_lshl_add_u64 v[34:35], v[18:19], 0, v[34:35]
	global_load_dwordx4 v[50:53], v[26:27], off
	global_load_dwordx4 v[54:57], v[34:35], off
	v_add_u32_e32 v26, s8, v42
	v_ashrrev_i32_e32 v27, 31, v26
	v_lshlrev_b64 v[26:27], 10, v[26:27]
	v_lshl_add_u64 v[26:27], v[18:19], 0, v[26:27]
	global_load_dwordx4 v[58:61], v[26:27], off
	v_add_u32_e32 v26, s8, v43
	v_ashrrev_i32_e32 v27, 31, v26
	v_lshlrev_b64 v[26:27], 10, v[26:27]
	v_lshl_add_u64 v[18:19], v[18:19], 0, v[26:27]
	global_load_dwordx4 v[62:65], v[18:19], off
	v_add_u32_e32 v18, 0, v144
	v_mul_lo_u32 v9, v9, s60
	v_add_u32_e32 v19, v18, v9
	v_cmp_gt_i32_e32 vcc, s62, v147
	s_waitcnt vmcnt(11)
	ds_write_b128 v19, v[0:3]
	v_mul_lo_u32 v2, v36, s60
	v_add_u32_e32 v0, v18, v2
	v_mul_lo_u32 v3, v42, s60
	s_waitcnt vmcnt(10)
	ds_write_b128 v0, v[4:7]
	v_add_u32_e32 v0, v18, v3
	v_mul_lo_u32 v4, v43, s60
	s_waitcnt vmcnt(9)
	ds_write_b128 v0, v[10:13]
	v_add_u32_e32 v0, v18, v4
	s_waitcnt vmcnt(8)
	ds_write_b128 v0, v[14:17]
	v_mad_u64_u32 v[0:1], s[6:7], v66, s60, v[18:19]
	s_waitcnt vmcnt(7)
	ds_write_b128 v0, v[22:25]
	v_mad_u64_u32 v[0:1], s[6:7], v67, s60, v[18:19]
	s_waitcnt vmcnt(6)
	ds_write_b128 v0, v[30:33]
	v_mad_u64_u32 v[0:1], s[6:7], v68, s60, v[18:19]
	v_and_b32_e32 v36, 31, v147
	s_waitcnt vmcnt(5)
	ds_write_b128 v0, v[38:41]
	v_mad_u64_u32 v[0:1], s[6:7], v69, s60, v[18:19]
	s_waitcnt vmcnt(4)
	ds_write_b128 v0, v[46:49]
	v_add_u32_e32 v0, 0, v9
	v_add3_u32 v0, v0, v144, s61
	s_waitcnt vmcnt(3)
	ds_write_b128 v0, v[50:53]
	v_add_u32_e32 v0, 0, v2
	v_add3_u32 v0, v0, v144, s61
	s_waitcnt vmcnt(2)
	ds_write_b128 v0, v[54:57]
	v_add_u32_e32 v0, 0, v3
	v_add3_u32 v0, v0, v144, s61
	s_waitcnt vmcnt(1)
	ds_write_b128 v0, v[58:61]
	v_add_u32_e32 v0, 0, v4
	v_add3_u32 v0, v0, v144, s61
	s_waitcnt vmcnt(0)
	ds_write_b128 v0, v[62:65]
	s_and_saveexec_b64 s[6:7], vcc
	s_cbranch_execz .LBB0_511
	v_cmp_ne_u32_e32 vcc, 31, v36
	v_mov_b32_e32 v0, 0xff800000
	s_and_saveexec_b64 s[8:9], vcc
	s_cbranch_execz .LBB0_510
	s_mul_i32 s41, s40, 15
	s_sub_i32 s41, s41, s34
	v_ashrrev_i32_e32 v0, 5, v147
	v_add_u32_e32 v1, s41, v8
	v_add3_u32 v0, v1, 7, v0
	v_mad_u64_u32 v[0:1], s[42:43], v0, 31, v[36:37]
	v_ashrrev_i32_e32 v1, 31, v0
	s_waitcnt lgkmcnt(0)
	v_lshl_add_u64 v[0:1], v[0:1], 2, s[24:25]
	global_load_dword v0, v[0:1], off

; __device__ __forceinline__ void na_item(const Params& p, int item, char* lds) {
;     ...
;   const int qtok = b * 2048 + r * 64 + n * 16 + lr;
;   bf16x8 qf[2];
;   qf[0] = *(const bf16x8*)(Q + (size_t)qtok * 512 + h * 64 + lq * 8);
;   qf[1] = *(const bf16x8*)(Q + (size_t)qtok * 512 + h * 64 + 32 + lq * 8);
;   __syncthreads();
;   const int band = (n == 0) ? 0 : (n == 1) ? 8 : (n == 2) ? 24 : 32;
;   f32x4 s[16];
; #pragma unroll
;   for (int ch = 0; ch < 8; ++ch)
; #pragma unroll
;     for (int ab = 0; ab < 2; ++ab) {
;       const int slot = 8 * (lr >> 2) + 4 * ab + (lr & 3);
;       const int krow = (half == 0) ? (ch * 64 + band + slot) : (512 + ch * 32 + slot);
;       f32x4 a = (f32x4){0.f, 0.f, 0.f, 0.f};
; #pragma unroll
;       for (int ks = 0; ks < 2; ++ks) {
;         const bf16x8 kf = *(const bf16x8*)(lds + krow * 144 + ks * 64 + lq * 16);
;         a = __builtin_amdgcn_mfma_f32_16x16x32_bf16(kf, qf[ks], a, 0, 0, 0);
;       }
;       s[ch * 2 + ab] = a;
;     }
.LBB0_517:
	s_or_b64 exec, exec, s[6:7]
	v_lshlrev_b32_e32 v9, 1, v173
	v_and_b32_e32 v10, 3, v147
	v_cmp_gt_u32_e32 vcc, s62, v147
	v_and_or_b32 v9, v9, 24, v10
	v_add_u32_e32 v18, 0, v158
	v_cndmask_b32_e32 v14, v157, v73, vcc
	v_add_u32_e32 v10, v14, v9
	v_mad_u32_u24 v15, v10, s60, v18
	ds_read_b128 v[10:13], v15
	v_or_b32_e32 v19, 4, v9
	v_add_u32_e32 v22, v14, v19
	ds_read_b128 v[14:17], v15 offset:64
	v_mad_u32_u24 v26, v22, s60, v18
	s_waitcnt vmcnt(1) lgkmcnt(1)
	v_mfma_f32_16x16x32_bf16 v[10:13], v[10:13], v[4:7], 0
	ds_read_b128 v[22:25], v26
	ds_read_b128 v[30:33], v26 offset:64
	s_lshl_b32 s6, s38, 9
	s_or_b32 s6, s6, s40
	s_waitcnt vmcnt(0) lgkmcnt(2)
	v_mfma_f32_16x16x32_bf16 v[140:143], v[14:17], v[0:3], v[10:13]
	v_lshlrev_b32_e32 v144, 7, v8
	v_ashrrev_i32_e32 v174, 6, v37
	v_ashrrev_i32_e32 v175, 6, v44
	v_or_b32_e32 v10, 64, v73
	v_cndmask_b32_e32 v26, v162, v10, vcc
	v_add_u32_e32 v10, v26, v9
	v_mad_u32_u24 v14, v10, s60, v18
	ds_read_b128 v[10:13], v14
	ds_read_b128 v[14:17], v14 offset:64
	s_waitcnt lgkmcnt(1)
	v_mfma_f32_16x16x32_bf16 v[10:13], v[10:13], v[4:7], 0
	v_ashrrev_i32_e32 v176, 6, v45
	v_ashrrev_i32_e32 v177, 6, v20
	v_ashrrev_i32_e32 v178, 6, v21
	v_mfma_f32_16x16x32_bf16 v[22:25], v[22:25], v[4:7], 0
	v_ashrrev_i32_e32 v179, 6, v28
	v_ashrrev_i32_e32 v180, 6, v29
	v_add_u32_e32 v20, s6, v178
	s_waitcnt lgkmcnt(0)
	v_mfma_f32_16x16x32_bf16 v[132:135], v[14:17], v[0:3], v[10:13]
	v_add_u32_e32 v28, s6, v180
	v_ashrrev_i32_e32 v21, 31, v20
	v_ashrrev_i32_e32 v29, 31, v28
	v_add_u32_e32 v10, v26, v19
	v_mad_u32_u24 v14, v10, s60, v18
	v_mfma_f32_16x16x32_bf16 v[136:139], v[30:33], v[0:3], v[22:25]
	ds_read_b128 v[10:13], v14
	ds_read_b128 v[14:17], v14 offset:64
	v_lshlrev_b64 v[20:21], 12, v[20:21]
	v_or_b32_e32 v22, 0x80, v73
	v_cndmask_b32_e32 v26, v163, v22, vcc
	v_add_u32_e32 v22, v26, v9
	v_mad_u32_u24 v27, v22, s60, v18
	s_waitcnt lgkmcnt(1)
	v_mfma_f32_16x16x32_bf16 v[10:13], v[10:13], v[4:7], 0
	ds_read_b128 v[22:25], v27
	v_lshlrev_b64 v[28:29], 12, v[28:29]
	v_lshl_add_u64 v[20:21], s[10:11], 0, v[20:21]
	s_waitcnt lgkmcnt(1)
	v_mfma_f32_16x16x32_bf16 v[124:127], v[14:17], v[0:3], v[10:13]
	v_lshl_add_u64 v[28:29], s[10:11], 0, v[28:29]
	v_lshlrev_b32_e32 v160, 4, v159
	v_mov_b32_e32 v161, v145
	ds_read_b128 v[10:13], v27 offset:64
	s_waitcnt lgkmcnt(1)
	v_mfma_f32_16x16x32_bf16 v[14:17], v[22:25], v[4:7], 0
	v_or_b32_e32 v22, 0xc0, v73
	v_lshl_add_u64 v[20:21], v[20:21], 0, v[144:145]
	v_lshl_add_u64 v[28:29], v[28:29], 0, v[144:145]
	s_waitcnt lgkmcnt(0)
	v_mfma_f32_16x16x32_bf16 v[116:119], v[10:13], v[0:3], v[14:17]
	v_add_u32_e32 v10, v26, v19
	s_nop 1
	v_mad_u32_u24 v14, v10, s60, v18
	ds_read_b128 v[10:13], v14
	ds_read_b128 v[14:17], v14 offset:64
	v_cndmask_b32_e32 v26, v164, v22, vcc
	v_add_u32_e32 v22, v26, v9
	v_mad_u32_u24 v27, v22, s60, v18
	s_waitcnt lgkmcnt(1)
	v_mfma_f32_16x16x32_bf16 v[10:13], v[10:13], v[4:7], 0
	ds_read_b128 v[22:25], v27
	v_lshl_add_u64 v[20:21], v[20:21], 0, v[160:161]
	v_lshl_add_u64 v[28:29], v[28:29], 0, v[160:161]
	s_waitcnt lgkmcnt(1)
	v_mfma_f32_16x16x32_bf16 v[108:111], v[14:17], v[0:3], v[10:13]
	v_ashrrev_i32_e32 v181, 5, v37
	v_ashrrev_i32_e32 v182, 5, v44
	v_ashrrev_i32_e32 v183, 5, v45
	ds_read_b128 v[10:13], v27 offset:64
	s_waitcnt lgkmcnt(1)
	v_mfma_f32_16x16x32_bf16 v[14:17], v[22:25], v[4:7], 0
	v_or_b32_e32 v22, 0x100, v73
	v_add_u32_e32 v46, s6, v182
	v_add_u32_e32 v44, s6, v183
	s_waitcnt lgkmcnt(0)
	v_mfma_f32_16x16x32_bf16 v[100:103], v[10:13], v[0:3], v[14:17]
	v_add_u32_e32 v10, v26, v19
	s_nop 1
	v_mad_u32_u24 v14, v10, s60, v18
	v_cndmask_b32_e32 v26, v165, v22, vcc
	ds_read_b128 v[10:13], v14
	ds_read_b128 v[14:17], v14 offset:64
	v_add_u32_e32 v22, v26, v9
	v_mad_u32_u24 v27, v22, s60, v18
	ds_read_b128 v[22:25], v27
	s_waitcnt lgkmcnt(2)
	v_mfma_f32_16x16x32_bf16 v[10:13], v[10:13], v[4:7], 0
	v_ashrrev_i32_e32 v47, 31, v46
	v_ashrrev_i32_e32 v45, 31, v44
	v_lshlrev_b64 v[46:47], 9, v[46:47]
	s_waitcnt lgkmcnt(1)
	v_mfma_f32_16x16x32_bf16 v[88:91], v[14:17], v[0:3], v[10:13]
	v_lshlrev_b64 v[44:45], 9, v[44:45]
	v_lshl_add_u64 v[46:47], s[18:19], 0, v[46:47]
	v_lshl_add_u64 v[44:45], s[18:19], 0, v[44:45]
	ds_read_b128 v[10:13], v27 offset:64
	s_waitcnt lgkmcnt(1)
	v_mfma_f32_16x16x32_bf16 v[14:17], v[22:25], v[4:7], 0
	v_add_u32_e32 v22, v26, v19
	v_mad_u32_u24 v26, v22, s60, v18
	ds_read_b128 v[22:25], v26
	s_waitcnt lgkmcnt(1)
	v_mfma_f32_16x16x32_bf16 v[80:83], v[10:13], v[0:3], v[14:17]
	ds_read_b128 v[10:13], v26 offset:64
	v_or_b32_e32 v26, 0x140, v73
	v_add_u32_e32 v184, v73, v146
	s_waitcnt lgkmcnt(1)
	v_mfma_f32_16x16x32_bf16 v[14:17], v[22:25], v[4:7], 0
	v_cndmask_b32_e32 v22, v166, v26, vcc
	v_add_u32_e32 v23, v22, v9
	v_mad_u32_u24 v23, v23, s60, v18
	s_waitcnt lgkmcnt(0)
	v_mfma_f32_16x16x32_bf16 v[76:79], v[10:13], v[0:3], v[14:17]
	ds_read_b128 v[10:13], v23
	s_nop 1
	ds_read_b128 v[14:17], v23 offset:64
	v_add_u32_e32 v22, v22, v19
	v_mad_u32_u24 v26, v22, s60, v18
	s_waitcnt lgkmcnt(1)
	v_mfma_f32_16x16x32_bf16 v[10:13], v[10:13], v[4:7], 0
	ds_read_b128 v[22:25], v26
	ds_read_b128 v[30:33], v26 offset:64
	s_waitcnt lgkmcnt(2)
	v_mfma_f32_16x16x32_bf16 v[68:71], v[14:17], v[0:3], v[10:13]
	s_nop 3
	v_or_b32_e32 v10, 0x180, v73
	v_cndmask_b32_e32 v26, v167, v10, vcc
	v_add_u32_e32 v14, v26, v9
	s_waitcnt lgkmcnt(1)
	v_mfma_f32_16x16x32_bf16 v[10:13], v[22:25], v[4:7], 0
	v_mad_u32_u24 v22, v14, s60, v18
	ds_read_b128 v[14:17], v22
	ds_read_b128 v[22:25], v22 offset:64
	s_waitcnt lgkmcnt(2)
	v_mfma_f32_16x16x32_bf16 v[64:67], v[30:33], v[0:3], v[10:13]
	s_nop 2
	v_add_u32_e32 v10, v26, v19
	v_mad_u32_u24 v26, v10, s60, v18
	ds_read_b128 v[10:13], v26
	ds_read_b128 v[30:33], v26 offset:64
	s_waitcnt lgkmcnt(3)
; __device__ __forceinline__ void na_item(const Params& p, int item, char* lds) {
;     ...
;   NA_VL(0) NA_VL(1) NA_VL(2) NA_VL(3) NA_VL(4) NA_VL(5) NA_VL(6) NA_VL(7)
;   NA_VC(0) NA_VC(1) NA_VC(2) NA_VC(3)
;   if (half == 0) {
;     const int qc = n * 16 + lr;
;     const int wstart = min(max(qc - 8, 0), 48);
; #pragma unroll
;     for (int ch = 0; ch < 8; ++ch)
; #pragma unroll
;       for (int ab = 0; ab < 2; ++ab)
; #pragma unroll
;         for (int e = 0; e < 4; ++e) {
;           const int kcol = band + 8 * lq + 4 * ab + e;
;           const bool inw = (kcol >= wstart) && (kcol < wstart + 16);
;           const int ci = min(max(kcol - qc + 15, 0), 30);
;           const float bv = rp[ch * 32 + ci];
;           s[ch * 2 + ab][e] = inw ? (s[ch * 2 + ab][e] + bv) : -INFINITY;
;         }
;   }
	v_mfma_f32_16x16x32_bf16 v[14:17], v[14:17], v[4:7], 0
	v_or_b32_e32 v26, 0x1c0, v73
	v_cndmask_b32_e32 v26, v168, v26, vcc
	v_add_u32_e32 v9, v26, v9
	v_mad_u32_u24 v9, v9, s60, v18
	s_waitcnt lgkmcnt(2)
	v_mfma_f32_16x16x32_bf16 v[60:63], v[22:25], v[0:3], v[14:17]
	ds_read_b128 v[22:25], v9 offset:64
	s_nop 1
	ds_read_b128 v[14:17], v9
	s_waitcnt lgkmcnt(3)
	v_mfma_f32_16x16x32_bf16 v[10:13], v[10:13], v[4:7], 0
	v_add_u32_e32 v9, v26, v19
	v_mad_u32_u24 v9, v9, s60, v18
	v_add_u32_e32 v18, s6, v171
	s_waitcnt lgkmcnt(0)
	v_mfma_f32_16x16x32_bf16 v[14:17], v[14:17], v[4:7], 0
	v_ashrrev_i32_e32 v19, 31, v18
	v_mfma_f32_16x16x32_bf16 v[56:59], v[30:33], v[0:3], v[10:13]
	s_nop 2
	ds_read_b128 v[10:13], v9
	ds_read_b128 v[84:87], v9 offset:64
	v_add_u32_e32 v30, s6, v179
	v_ashrrev_i32_e32 v31, 31, v30
	v_mfma_f32_16x16x32_bf16 v[52:55], v[22:25], v[0:3], v[14:17]
	v_add_u32_e32 v22, s6, v177
	v_ashrrev_i32_e32 v23, 31, v22
	v_lshlrev_b64 v[22:23], 12, v[22:23]
	v_lshlrev_b64 v[14:15], 12, v[18:19]
	v_lshl_add_u64 v[14:15], s[10:11], 0, v[14:15]
	s_waitcnt lgkmcnt(1)
	v_mfma_f32_16x16x32_bf16 v[92:95], v[10:13], v[4:7], 0
	v_lshl_add_u64 v[4:5], v[14:15], 0, v[144:145]
	v_add_u32_e32 v6, s6, v174
	v_add_u32_e32 v12, s6, v175
	v_add_u32_e32 v14, s6, v176
	v_ashrrev_i32_e32 v7, 31, v6
	v_ashrrev_i32_e32 v13, 31, v12
	v_ashrrev_i32_e32 v15, 31, v14
	v_lshlrev_b64 v[6:7], 12, v[6:7]
	v_lshlrev_b64 v[12:13], 12, v[12:13]
	v_lshlrev_b64 v[14:15], 12, v[14:15]
	v_lshlrev_b64 v[30:31], 12, v[30:31]
	v_lshl_add_u64 v[6:7], s[10:11], 0, v[6:7]
	v_lshl_add_u64 v[12:13], s[10:11], 0, v[12:13]
	v_lshl_add_u64 v[14:15], s[10:11], 0, v[14:15]
	v_lshl_add_u64 v[22:23], s[10:11], 0, v[22:23]
	v_lshl_add_u64 v[30:31], s[10:11], 0, v[30:31]
	v_lshl_add_u64 v[6:7], v[6:7], 0, v[144:145]
	v_lshl_add_u64 v[12:13], v[12:13], 0, v[144:145]
	v_lshl_add_u64 v[14:15], v[14:15], 0, v[144:145]
	v_lshl_add_u64 v[22:23], v[22:23], 0, v[144:145]
	v_lshl_add_u64 v[30:31], v[30:31], 0, v[144:145]
	v_lshl_add_u64 v[4:5], v[4:5], 0, v[160:161]
	v_lshl_add_u64 v[6:7], v[6:7], 0, v[160:161]
	v_lshl_add_u64 v[12:13], v[12:13], 0, v[160:161]
	v_lshl_add_u64 v[14:15], v[14:15], 0, v[160:161]
	v_lshl_add_u64 v[22:23], v[22:23], 0, v[160:161]
	v_lshl_add_u64 v[30:31], v[30:31], 0, v[160:161]
	v_ashrrev_i32_e32 v161, 5, v147
	v_add_u32_e32 v38, s6, v161
	v_lshlrev_b32_e32 v144, 4, v36
	v_add_u32_e32 v36, s6, v181
	v_ashrrev_i32_e32 v39, 31, v38
	v_ashrrev_i32_e32 v37, 31, v36
	v_lshlrev_b64 v[38:39], 9, v[38:39]
	v_lshlrev_b64 v[36:37], 9, v[36:37]
	v_lshl_add_u64 v[38:39], s[18:19], 0, v[38:39]
	v_lshl_add_u64 v[36:37], s[18:19], 0, v[36:37]
	v_lshl_add_u64 v[38:39], v[38:39], 0, v[144:145]
	v_lshl_add_u64 v[36:37], v[36:37], 0, v[144:145]
	v_lshl_add_u64 v[46:47], v[46:47], 0, v[144:145]
	v_lshl_add_u64 v[44:45], v[44:45], 0, v[144:145]
	global_load_dwordx4 v[8:11], v[4:5], off
	s_nop 0
	global_load_dwordx4 v[4:7], v[6:7], off
	s_nop 0
	global_load_dwordx4 v[16:19], v[12:13], off
	s_nop 0
	global_load_dwordx4 v[12:15], v[14:15], off
	s_nop 0
	global_load_dwordx4 v[24:27], v[22:23], off
	s_nop 0
	global_load_dwordx4 v[20:23], v[20:21], off
	s_nop 0
	global_load_dwordx4 v[32:35], v[30:31], off
	s_nop 0
	global_load_dwordx4 v[28:31], v[28:29], off
	s_nop 0
	global_load_dwordx4 v[40:43], v[38:39], off
	s_nop 0
	global_load_dwordx4 v[36:39], v[36:37], off
	s_nop 0
	global_load_dwordx4 v[48:51], v[46:47], off
	s_nop 0
	global_load_dwordx4 v[44:47], v[44:45], off
	s_waitcnt lgkmcnt(0)
	v_mfma_f32_16x16x32_bf16 v[0:3], v[84:87], v[0:3], v[92:95]
	v_cmp_lt_u32_e64 s[6:7], s63, v147
	s_and_saveexec_b64 s[8:9], s[6:7]
	s_xor_b64 s[6:7], exec, s[8:9]
	v_add_u32_e32 v184, v73, v146
	s_or_saveexec_b64 s[38:39], s[6:7]
	v_mov_b32_e32 v185, 0x210
	s_xor_b64 exec, exec, s[38:39]
	s_cbranch_execz .LBB0_649
	v_or_b32_e32 v92, v72, v173
	v_sub_u32_e64 v72, v92, 8 clamp
	v_min_u32_e32 v93, 48, v72
	v_add_u32_e32 v94, 16, v93
	v_add_u32_e32 v243, 0, v184
	v_cmp_ge_u32_e64 s[6:7], v243, v93
	v_cmp_lt_u32_e64 s[8:9], v243, v94
	v_sub_u32_e32 v244, v243, v92
	s_and_b64 s[98:99], s[6:7], s[8:9]
	v_max_i32_e32 v244, -15, v244
	v_add_u32_e32 v244, 15, v244
	v_min_u32_e32 v244, 30, v244
	v_cndmask_b32_e64 v244, 31, v244, s[98:99]
	v_lshl_add_u32 v244, v244, 2, 0
	v_add_u32_e32 v235, 0x1b000, v244
	v_add_u32_e32 v243, 1, v184
	v_cmp_ge_u32_e64 s[6:7], v243, v93
	v_cmp_lt_u32_e64 s[8:9], v243, v94
	v_sub_u32_e32 v244, v243, v92
	s_and_b64 s[98:99], s[6:7], s[8:9]
	v_max_i32_e32 v244, -15, v244
	v_add_u32_e32 v244, 15, v244
	v_min_u32_e32 v244, 30, v244
	v_cndmask_b32_e64 v244, 31, v244, s[98:99]
	v_lshl_add_u32 v244, v244, 2, 0
	v_add_u32_e32 v236, 0x1b000, v244
	v_add_u32_e32 v243, 2, v184
	v_cmp_ge_u32_e64 s[6:7], v243, v93
	v_cmp_lt_u32_e64 s[8:9], v243, v94
	v_sub_u32_e32 v244, v243, v92
	s_and_b64 s[98:99], s[6:7], s[8:9]
	v_max_i32_e32 v244, -15, v244
	v_add_u32_e32 v244, 15, v244
	v_min_u32_e32 v244, 30, v244
	v_cndmask_b32_e64 v244, 31, v244, s[98:99]
	v_lshl_add_u32 v244, v244, 2, 0
	v_add_u32_e32 v237, 0x1b000, v244
	v_add_u32_e32 v243, 3, v184
	v_cmp_ge_u32_e64 s[6:7], v243, v93
	v_cmp_lt_u32_e64 s[8:9], v243, v94
	v_sub_u32_e32 v244, v243, v92
	s_and_b64 s[98:99], s[6:7], s[8:9]
	v_max_i32_e32 v244, -15, v244
	v_add_u32_e32 v244, 15, v244
	v_min_u32_e32 v244, 30, v244
	v_cndmask_b32_e64 v244, 31, v244, s[98:99]
	v_lshl_add_u32 v244, v244, 2, 0
	v_add_u32_e32 v238, 0x1b000, v244
	v_add_u32_e32 v243, 4, v184
	v_cmp_ge_u32_e64 s[6:7], v243, v93
	v_cmp_lt_u32_e64 s[8:9], v243, v94
	v_sub_u32_e32 v244, v243, v92
	s_and_b64 s[98:99], s[6:7], s[8:9]
	v_max_i32_e32 v244, -15, v244
	v_add_u32_e32 v244, 15, v244
; __device__ __forceinline__ void na_item(const Params& p, int item, char* lds) {
;     ...
;   if (half == 0) {
;     const int qc = n * 16 + lr;
;     const int wstart = min(max(qc - 8, 0), 48);
; #pragma unroll
;     for (int ch = 0; ch < 8; ++ch)
; #pragma unroll
;       for (int ab = 0; ab < 2; ++ab)
; #pragma unroll
;         for (int e = 0; e < 4; ++e) {
;           const int kcol = band + 8 * lq + 4 * ab + e;
;           const bool inw = (kcol >= wstart) && (kcol < wstart + 16);
;           const int ci = min(max(kcol - qc + 15, 0), 30);
;           const float bv = rp[ch * 32 + ci];
;           s[ch * 2 + ab][e] = inw ? (s[ch * 2 + ab][e] + bv) : -INFINITY;
;         }
;   }
	v_min_u32_e32 v244, 30, v244
	v_cndmask_b32_e64 v244, 31, v244, s[98:99]
	v_lshl_add_u32 v244, v244, 2, 0
	v_add_u32_e32 v239, 0x1b000, v244
	v_add_u32_e32 v243, 5, v184
	v_cmp_ge_u32_e64 s[6:7], v243, v93
	v_cmp_lt_u32_e64 s[8:9], v243, v94
	v_sub_u32_e32 v244, v243, v92
	s_and_b64 s[98:99], s[6:7], s[8:9]
	v_max_i32_e32 v244, -15, v244
	v_add_u32_e32 v244, 15, v244
	v_min_u32_e32 v244, 30, v244
	v_cndmask_b32_e64 v244, 31, v244, s[98:99]
	v_lshl_add_u32 v244, v244, 2, 0
	v_add_u32_e32 v240, 0x1b000, v244
	v_add_u32_e32 v243, 6, v184
	v_cmp_ge_u32_e64 s[6:7], v243, v93
	v_cmp_lt_u32_e64 s[8:9], v243, v94
	v_sub_u32_e32 v244, v243, v92
	s_and_b64 s[98:99], s[6:7], s[8:9]
	v_max_i32_e32 v244, -15, v244
	v_add_u32_e32 v244, 15, v244
	v_min_u32_e32 v244, 30, v244
	v_cndmask_b32_e64 v244, 31, v244, s[98:99]
	v_lshl_add_u32 v244, v244, 2, 0
	v_add_u32_e32 v241, 0x1b000, v244
	v_add_u32_e32 v243, 7, v184
	v_cmp_ge_u32_e64 s[6:7], v243, v93
	v_cmp_lt_u32_e64 s[8:9], v243, v94
	v_sub_u32_e32 v244, v243, v92
	s_and_b64 s[98:99], s[6:7], s[8:9]
	v_max_i32_e32 v244, -15, v244
	v_add_u32_e32 v244, 15, v244
	v_min_u32_e32 v244, 30, v244
	v_cndmask_b32_e64 v244, 31, v244, s[98:99]
	v_lshl_add_u32 v244, v244, 2, 0
	v_add_u32_e32 v242, 0x1b000, v244
	v_cmp_ge_u32_e64 s[6:7], v184, v93
	v_cmp_lt_u32_e64 s[8:9], v184, v94
	v_sub_u32_e32 v72, v184, v92
	s_and_b64 s[40:41], s[6:7], s[8:9]
	v_mov_b32_e32 v73, 0xff800000
	v_max_i32_e32 v185, -15, v72
	v_mov_b32_e32 v72, 0xff800000
	ds_read_b32 v245, v235
	ds_read_b32 v246, v236
	ds_read_b32 v247, v237
	ds_read_b32 v248, v238
	ds_read_b32 v249, v239
	ds_read_b32 v250, v240
	ds_read_b32 v251, v241
	ds_read_b32 v252, v242
	ds_read_b32 v253, v235 offset:128
	ds_read_b32 v254, v236 offset:128
	ds_read_b32 v255, v237 offset:128
	s_waitcnt lgkmcnt(0)
	v_add_f32_e32 v72, v140, v245
	v_or_b32_e32 v74, 1, v184
	v_cmp_ge_u32_e64 s[6:7], v74, v93
	v_cmp_lt_u32_e64 s[8:9], v74, v94
	v_sub_u32_e32 v74, v74, v92
	s_and_b64 s[42:43], s[6:7], s[8:9]
	v_max_i32_e32 v140, -15, v74
	v_add_f32_e32 v73, v141, v246
	v_or_b32_e32 v74, 2, v184
	v_cmp_ge_u32_e64 s[6:7], v74, v93
	v_cmp_lt_u32_e64 s[8:9], v74, v94
	v_sub_u32_e32 v74, v74, v92
	s_and_b64 s[44:45], s[6:7], s[8:9]
	v_mov_b32_e32 v75, 0xff800000
	v_max_i32_e32 v141, -15, v74
	v_mov_b32_e32 v74, 0xff800000
	v_add_f32_e32 v74, v142, v247
	v_or_b32_e32 v84, 3, v184
	v_cmp_ge_u32_e64 s[6:7], v84, v93
	v_cmp_lt_u32_e64 s[8:9], v84, v94
	v_sub_u32_e32 v84, v84, v92
	s_and_b64 s[46:47], s[6:7], s[8:9]
	v_max_i32_e32 v142, -15, v84
	v_add_f32_e32 v75, v143, v248
	v_or_b32_e32 v84, 4, v184
	v_cmp_ge_u32_e64 s[6:7], v84, v93
	v_cmp_lt_u32_e64 s[8:9], v84, v94
	v_sub_u32_e32 v84, v84, v92
	s_and_b64 s[52:53], s[6:7], s[8:9]
	v_mov_b32_e32 v85, 0xff800000
	v_max_i32_e32 v143, -15, v84
	v_mov_b32_e32 v84, 0xff800000
	v_add_f32_e32 v84, v136, v249
	v_or_b32_e32 v86, 5, v184
	v_cmp_ge_u32_e64 s[6:7], v86, v93
	v_cmp_lt_u32_e64 s[8:9], v86, v94
	v_sub_u32_e32 v86, v86, v92
	s_and_b64 s[54:55], s[6:7], s[8:9]
	v_max_i32_e32 v136, -15, v86
	v_add_f32_e32 v85, v137, v250
	v_or_b32_e32 v86, 6, v184
	v_cmp_ge_u32_e64 s[6:7], v86, v93
	v_cmp_lt_u32_e64 s[8:9], v86, v94
	v_sub_u32_e32 v86, v86, v92
	s_and_b64 s[56:57], s[6:7], s[8:9]
	v_mov_b32_e32 v87, 0xff800000
	v_max_i32_e32 v137, -15, v86
	v_mov_b32_e32 v86, 0xff800000
	v_add_f32_e32 v86, v138, v251
	v_or_b32_e32 v95, 7, v184
	v_cmp_ge_u32_e64 s[6:7], v95, v93
	v_cmp_lt_u32_e64 s[8:9], v95, v94
	v_sub_u32_e32 v92, v95, v92
	s_and_b64 s[6:7], s[6:7], s[8:9]
	v_max_i32_e32 v138, -15, v92
	v_add_f32_e32 v87, v139, v252
	v_mov_b32_e32 v93, 0xff800000
	v_mov_b32_e32 v92, 0xff800000
	v_add_f32_e32 v92, v132, v253
	v_add_f32_e32 v93, v133, v254
	v_mov_b32_e32 v95, 0xff800000
	v_mov_b32_e32 v94, 0xff800000
	v_add_f32_e32 v94, v134, v255
	ds_read_b32 v245, v238 offset:128
	ds_read_b32 v246, v239 offset:128
	ds_read_b32 v247, v240 offset:128
	ds_read_b32 v248, v241 offset:128
	ds_read_b32 v249, v242 offset:128
	ds_read_b32 v250, v235 offset:256
	ds_read_b32 v251, v236 offset:256
	ds_read_b32 v252, v237 offset:256
	ds_read_b32 v253, v238 offset:256
	ds_read_b32 v254, v239 offset:256
	ds_read_b32 v255, v240 offset:256
	s_waitcnt lgkmcnt(0)
	v_add_f32_e32 v95, v135, v245
	v_mov_b32_e32 v97, 0xff800000
	v_mov_b32_e32 v96, 0xff800000
	v_add_f32_e32 v96, v124, v246
	v_add_f32_e32 v97, v125, v247
	v_mov_b32_e32 v99, 0xff800000
	v_mov_b32_e32 v98, 0xff800000
	v_add_f32_e32 v98, v126, v248
	v_add_f32_e32 v99, v127, v249
	v_mov_b32_e32 v105, 0xff800000
	v_mov_b32_e32 v104, 0xff800000
	v_add_f32_e32 v104, v116, v250
	v_add_f32_e32 v105, v117, v251
	v_mov_b32_e32 v107, 0xff800000
	v_mov_b32_e32 v106, 0xff800000
	v_add_f32_e32 v106, v118, v252
	v_add_f32_e32 v107, v119, v253
	v_mov_b32_e32 v113, 0xff800000
	v_mov_b32_e32 v112, 0xff800000
	v_add_f32_e32 v112, v108, v254
	v_add_f32_e32 v113, v109, v255
	v_mov_b32_e32 v115, 0xff800000
	v_mov_b32_e32 v114, 0xff800000
	ds_read_b32 v245, v241 offset:256
	ds_read_b32 v246, v242 offset:256
	ds_read_b32 v247, v235 offset:384
	ds_read_b32 v248, v236 offset:384
	ds_read_b32 v249, v237 offset:384
	ds_read_b32 v250, v238 offset:384
	ds_read_b32 v251, v239 offset:384
	ds_read_b32 v252, v240 offset:384
	ds_read_b32 v253, v241 offset:384
	ds_read_b32 v254, v242 offset:384
	ds_read_b32 v255, v235 offset:512
	s_waitcnt lgkmcnt(0)
; __device__ __forceinline__ void na_item(const Params& p, int item, char* lds) {
;     ...
;   if (half == 0) {
;     const int qc = n * 16 + lr;
;     const int wstart = min(max(qc - 8, 0), 48);
; #pragma unroll
;     for (int ch = 0; ch < 8; ++ch)
; #pragma unroll
;       for (int ab = 0; ab < 2; ++ab)
; #pragma unroll
;         for (int e = 0; e < 4; ++e) {
;           const int kcol = band + 8 * lq + 4 * ab + e;
;           const bool inw = (kcol >= wstart) && (kcol < wstart + 16);
;           const int ci = min(max(kcol - qc + 15, 0), 30);
;           const float bv = rp[ch * 32 + ci];
;           s[ch * 2 + ab][e] = inw ? (s[ch * 2 + ab][e] + bv) : -INFINITY;
;         }
;   }
	v_add_f32_e32 v114, v110, v245
	v_add_f32_e32 v115, v111, v246
	v_mov_b32_e32 v121, 0xff800000
	v_mov_b32_e32 v120, 0xff800000
	v_add_f32_e32 v120, v100, v247
	v_add_f32_e32 v121, v101, v248
	v_mov_b32_e32 v123, 0xff800000
	v_mov_b32_e32 v122, 0xff800000
	v_add_f32_e32 v122, v102, v249
	v_add_f32_e32 v123, v103, v250
	v_mov_b32_e32 v129, 0xff800000
	v_mov_b32_e32 v128, 0xff800000
	v_add_f32_e32 v128, v88, v251
	v_add_f32_e32 v129, v89, v252
	v_mov_b32_e32 v131, 0xff800000
	v_mov_b32_e32 v130, 0xff800000
	v_add_f32_e32 v130, v90, v253
	v_add_f32_e32 v131, v91, v254
	v_mov_b32_e32 v89, 0xff800000
	v_mov_b32_e32 v88, 0xff800000
	v_add_f32_e32 v88, v80, v255
	ds_read_b32 v245, v236 offset:512
	ds_read_b32 v246, v237 offset:512
	ds_read_b32 v247, v238 offset:512
	ds_read_b32 v248, v239 offset:512
	ds_read_b32 v249, v240 offset:512
	ds_read_b32 v250, v241 offset:512
	ds_read_b32 v251, v242 offset:512
	ds_read_b32 v252, v235 offset:640
	ds_read_b32 v253, v236 offset:640
	ds_read_b32 v254, v237 offset:640
	ds_read_b32 v255, v238 offset:640
	s_waitcnt lgkmcnt(0)
	v_add_f32_e32 v89, v81, v245
	v_mov_b32_e32 v91, 0xff800000
	v_mov_b32_e32 v90, 0xff800000
	v_add_f32_e32 v90, v82, v246
	v_add_f32_e32 v91, v83, v247
	v_mov_b32_e32 v81, 0xff800000
	v_mov_b32_e32 v80, 0xff800000
	v_add_f32_e32 v80, v76, v248
	v_add_f32_e32 v81, v77, v249
	v_mov_b32_e32 v83, 0xff800000
	v_mov_b32_e32 v82, 0xff800000
	v_add_f32_e32 v82, v78, v250
	v_add_f32_e32 v83, v79, v251
	v_mov_b32_e32 v77, 0xff800000
	v_mov_b32_e32 v76, 0xff800000
	v_add_f32_e32 v76, v68, v252
	v_add_f32_e32 v77, v69, v253
	v_mov_b32_e32 v79, 0xff800000
	v_mov_b32_e32 v78, 0xff800000
	v_add_f32_e32 v78, v70, v254
	v_add_f32_e32 v79, v71, v255
	v_mov_b32_e32 v69, 0xff800000
	v_mov_b32_e32 v68, 0xff800000
	ds_read_b32 v245, v239 offset:640
	ds_read_b32 v246, v240 offset:640
	ds_read_b32 v247, v241 offset:640
	ds_read_b32 v248, v242 offset:640
	ds_read_b32 v249, v235 offset:768
	ds_read_b32 v250, v236 offset:768
	ds_read_b32 v251, v237 offset:768
	ds_read_b32 v252, v238 offset:768
	ds_read_b32 v253, v239 offset:768
	ds_read_b32 v254, v240 offset:768
	ds_read_b32 v255, v241 offset:768
	s_waitcnt lgkmcnt(0)
	v_add_f32_e32 v68, v64, v245
	v_add_f32_e32 v69, v65, v246
	v_mov_b32_e32 v71, 0xff800000
	v_mov_b32_e32 v70, 0xff800000
	v_add_f32_e32 v70, v66, v247
	v_add_f32_e32 v71, v67, v248
	v_mov_b32_e32 v65, 0xff800000
	v_mov_b32_e32 v64, 0xff800000
	v_add_f32_e32 v64, v60, v249
	v_add_f32_e32 v65, v61, v250
	v_mov_b32_e32 v67, 0xff800000
	v_mov_b32_e32 v66, 0xff800000
	v_add_f32_e32 v66, v62, v251
	v_add_f32_e32 v67, v63, v252
	v_mov_b32_e32 v61, 0xff800000
	v_mov_b32_e32 v60, 0xff800000
	v_add_f32_e32 v60, v56, v253
	v_add_f32_e32 v61, v57, v254
	v_mov_b32_e32 v63, 0xff800000
	v_mov_b32_e32 v62, 0xff800000
	v_add_f32_e32 v62, v58, v255
	ds_read_b32 v245, v242 offset:768
	ds_read_b32 v246, v235 offset:896
	ds_read_b32 v247, v236 offset:896
	ds_read_b32 v248, v237 offset:896
	ds_read_b32 v249, v238 offset:896
	ds_read_b32 v250, v239 offset:896
	ds_read_b32 v251, v240 offset:896
	ds_read_b32 v252, v241 offset:896
	ds_read_b32 v253, v242 offset:896
	s_waitcnt lgkmcnt(0)
	v_add_f32_e32 v63, v59, v245
	v_mov_b32_e32 v57, 0xff800000
	v_mov_b32_e32 v56, 0xff800000
	v_add_f32_e32 v56, v52, v246
	v_add_f32_e32 v57, v53, v247
	v_mov_b32_e32 v59, 0xff800000
	v_mov_b32_e32 v58, 0xff800000
	v_add_f32_e32 v58, v54, v248
	v_add_f32_e32 v59, v55, v249
	v_mov_b32_e32 v53, 0xff800000
	v_mov_b32_e32 v52, 0xff800000
	v_add_f32_e32 v52, v0, v250
	v_add_f32_e32 v53, v1, v251
	v_mov_b32_e32 v55, 0xff800000
	v_mov_b32_e32 v54, 0xff800000
	v_add_f32_e32 v54, v2, v252
	v_add_f32_e32 v55, v3, v253
	v_mov_b64_e32 v[0:1], v[52:53]
	v_mov_b64_e32 v[2:3], v[54:55]
	v_mov_b64_e32 v[52:53], v[56:57]
	v_mov_b64_e32 v[54:55], v[58:59]
	v_mov_b64_e32 v[56:57], v[60:61]
	v_mov_b64_e32 v[58:59], v[62:63]
	v_mov_b64_e32 v[60:61], v[64:65]
	v_mov_b64_e32 v[62:63], v[66:67]
	v_mov_b64_e32 v[64:65], v[68:69]
	v_mov_b64_e32 v[66:67], v[70:71]
	v_mov_b64_e32 v[68:69], v[76:77]
	v_mov_b64_e32 v[70:71], v[78:79]
	v_mov_b64_e32 v[76:77], v[80:81]
	v_mov_b64_e32 v[78:79], v[82:83]
	v_mov_b64_e32 v[80:81], v[88:89]
	v_mov_b64_e32 v[82:83], v[90:91]
	v_mov_b64_e32 v[142:143], v[74:75]
	v_mov_b64_e32 v[138:139], v[86:87]
	v_mov_b64_e32 v[134:135], v[94:95]
	v_mov_b64_e32 v[126:127], v[98:99]
	v_mov_b64_e32 v[118:119], v[106:107]
	v_mov_b64_e32 v[108:109], v[112:113]
	v_mov_b64_e32 v[100:101], v[120:121]
	v_mov_b64_e32 v[88:89], v[128:129]
	v_mov_b32_e32 v185, 0x410
	v_mov_b64_e32 v[140:141], v[72:73]
	v_mov_b64_e32 v[136:137], v[84:85]
	v_mov_b64_e32 v[132:133], v[92:93]
	v_mov_b64_e32 v[124:125], v[96:97]
	v_mov_b64_e32 v[116:117], v[104:105]
	v_mov_b64_e32 v[110:111], v[114:115]
	v_mov_b64_e32 v[102:103], v[122:123]
	v_mov_b64_e32 v[90:91], v[130:131]

; __global__ void __launch_bounds__(NTHR) fwd_megakernel(Params p) {
	.amdhsa_kernel _Z14fwd_megakernel6Params
		.amdhsa_group_segment_fixed_size 0
		.amdhsa_private_segment_fixed_size 0
		.amdhsa_kernarg_size 496
		.amdhsa_user_sgpr_count 2
		.amdhsa_user_sgpr_dispatch_ptr 0
		.amdhsa_user_sgpr_queue_ptr 0
		.amdhsa_user_sgpr_kernarg_segment_ptr 1
		.amdhsa_user_sgpr_dispatch_id 0
		.amdhsa_user_sgpr_kernarg_preload_length 0
		.amdhsa_user_sgpr_kernarg_preload_offset 0
		.amdhsa_user_sgpr_private_segment_size 0
		.amdhsa_uses_dynamic_stack 0
		.amdhsa_enable_private_segment 0
		.amdhsa_system_sgpr_workgroup_id_x 1
		.amdhsa_system_sgpr_workgroup_id_y 0
		.amdhsa_system_sgpr_workgroup_id_z 0
		.amdhsa_system_sgpr_workgroup_info 0
		.amdhsa_system_vgpr_workitem_id 2
		.amdhsa_next_free_vgpr 256
		.amdhsa_next_free_sgpr 100
		.amdhsa_accum_offset 256
		.amdhsa_reserve_vcc 1
		.amdhsa_float_round_mode_32 0
		.amdhsa_float_round_mode_16_64 0
		.amdhsa_float_denorm_mode_32 3
		.amdhsa_float_denorm_mode_16_64 3
		.amdhsa_dx10_clamp 1
		.amdhsa_ieee_mode 1
		.amdhsa_fp16_overflow 0
		.amdhsa_tg_split 0
		.amdhsa_exception_fp_ieee_invalid_op 0
		.amdhsa_exception_fp_denorm_src 0
		.amdhsa_exception_fp_ieee_div_zero 0
		.amdhsa_exception_fp_ieee_overflow 0
		.amdhsa_exception_fp_ieee_underflow 0
		.amdhsa_exception_fp_ieee_inexact 0
		.amdhsa_exception_int_div_zero 0
	.end_amdhsa_kernel

; __global__ void __launch_bounds__(NTHR) fwd_megakernel(Params p) {
amdhsa.kernels:
  - .agpr_count:     0
    .args:
      - .offset:         0
        .size:           240
        .value_kind:     by_value
      - .offset:         240
        .size:           4
        .value_kind:     hidden_block_count_x
      - .offset:         244
        .size:           4
        .value_kind:     hidden_block_count_y
      - .offset:         248
        .size:           4
        .value_kind:     hidden_block_count_z
      - .offset:         252
        .size:           2
        .value_kind:     hidden_group_size_x
      - .offset:         254
        .size:           2
        .value_kind:     hidden_group_size_y
      - .offset:         256
        .size:           2
        .value_kind:     hidden_group_size_z
      - .offset:         258
        .size:           2
        .value_kind:     hidden_remainder_x
      - .offset:         260
        .size:           2
        .value_kind:     hidden_remainder_y
      - .offset:         262
        .size:           2
        .value_kind:     hidden_remainder_z
      - .offset:         280
        .size:           8
        .value_kind:     hidden_global_offset_x
      - .offset:         288
        .size:           8
        .value_kind:     hidden_global_offset_y
      - .offset:         296
        .size:           8
        .value_kind:     hidden_global_offset_z
      - .offset:         304
        .size:           2
        .value_kind:     hidden_grid_dims
      - .offset:         328
        .size:           8
        .value_kind:     hidden_multigrid_sync_arg
      - .offset:         360
        .size:           4
        .value_kind:     hidden_dynamic_lds_size
    .group_segment_fixed_size: 0
    .kernarg_segment_align: 8
    .kernarg_segment_size: 496
    .language:       OpenCL C
    .language_version:
      - 2
      - 0
    .max_flat_workgroup_size: 512
    .name:           _Z14fwd_megakernel6Params
    .private_segment_fixed_size: 0
    .sgpr_count:     106
    .sgpr_spill_count: 52
    .symbol:         _Z14fwd_megakernel6Params.kd
    .uniform_work_group_size: 1
    .uses_dynamic_stack: false
    .vgpr_count:     256
    .vgpr_spill_count: 0
    .wavefront_size: 64
